# even layers: G1e->mixer barrier XCD-local too (G1e stores write-through, boundary conv tiles wait on TOP), on stack18
# speedup vs baseline: 1.0097x; 1.0010x over previous
; __device__ __forceinline__ unsigned xb_ld(unsigned* p)              { return __hip_atomic_load(p, __ATOMIC_RELAXED, __HIP_MEMORY_SCOPE_AGENT); }
; __device__ __forceinline__ unsigned xb_add(unsigned* p, unsigned v) { return __hip_atomic_fetch_add(p, v, __ATOMIC_RELAXED, __HIP_MEMORY_SCOPE_AGENT); }
; #define XB_SPIN(cond, bar) do { unsigned _sp = 0; while (cond) { __builtin_amdgcn_s_sleep(1); \
;     if ((++_sp & 255u) == 0u) { if (xb_ld(&(bar)[XB_TMO])) break; if (_sp > XB_SPIN_CAP) { atomicAdd(&(bar)[XB_TMO], 1u); break; } } } } while (0)
; __device__ __forceinline__ void xcd_barrier(const XcdBarrier& b) {
;     asm volatile("s_waitcnt vmcnt(0)" ::: "memory");
;     __syncthreads();
;     if (threadIdx.x == 0) {
;         unsigned* bar = b.bar;
;         __builtin_amdgcn_s_waitcnt(0);
;         unsigned nloc = b.st[0], nx = b.st[1];
;         if (nloc == 0u) { xcd_barrier_complete(bar, b.x, nloc, nx); b.st[0] = nloc; b.st[1] = nx; }
;         const unsigned old = xb_add(&bar[XB_XSUB(b.x)], 1u);
;         const unsigned gen = old / nloc;
;         if (old + 1u == (gen + 1u) * nloc) {
;             __builtin_amdgcn_fence(__ATOMIC_RELEASE, "agent");
;             asm volatile("s_waitcnt vmcnt(0)" ::: "memory");
;             const unsigned og = xb_add(&bar[XB_TOP], 1u);
;             const unsigned tg = og / nx;
;             if (og + 1u == (tg + 1u) * nx) xb_add(&bar[XB_TOPGEN], 1u);
;             else XB_SPIN(xb_ld(&bar[XB_TOPGEN]) == tg, bar);
;             __builtin_amdgcn_fence(__ATOMIC_ACQUIRE, "agent");
;             asm volatile("s_waitcnt vmcnt(0)" ::: "memory");
;         } else {
;             XB_SPIN(xb_ld(&bar[XB_TOPGEN]) == gen, bar);
;             __builtin_amdgcn_fence(__ATOMIC_ACQUIRE, "agent");
;             asm volatile("s_waitcnt vmcnt(0)" ::: "memory");
;         }
.LBB0_333:
	v_readlane_b32 s4, v253, 35
	v_readlane_b32 s5, v253, 36
	v_cvt_f32_u32_e32 v1, v2
	v_sub_u32_e32 v4, 0, v2
	v_rcp_iflag_f32_e32 v1, v1
	s_nop 1
	global_atomic_add v3, v177, v238, s[4:5] sc0
	v_mul_f32_e32 v1, 0x4f7ffffe, v1
	v_cvt_u32_f32_e32 v1, v1
	v_mul_lo_u32 v4, v4, v1
	v_mul_hi_u32 v4, v1, v4
	v_add_u32_e32 v1, v1, v4
	s_waitcnt vmcnt(0)
	v_mul_hi_u32 v1, v3, v1
	v_mul_lo_u32 v4, v1, v2
	v_sub_u32_e32 v4, v3, v4
	v_add_u32_e32 v5, 1, v1
	v_cmp_ge_u32_e32 vcc, v4, v2
	v_add_u32_e32 v3, 1, v3
	s_nop 0
	v_cndmask_b32_e32 v1, v1, v5, vcc
	v_sub_u32_e32 v5, v4, v2
	v_cndmask_b32_e32 v4, v4, v5, vcc
	v_add_u32_e32 v5, 1, v1
	v_cmp_ge_u32_e32 vcc, v4, v2
	s_nop 1
	v_cndmask_b32_e32 v1, v1, v5, vcc
	v_mul_lo_u32 v4, v2, v1
	v_add_u32_e32 v2, v4, v2
	v_cmp_ne_u32_e32 vcc, v3, v2
	s_waitcnt lgkmcnt(0)
	v_add_u32_e32 v4, 1, v1
	v_mul_lo_u32 v4, v4, v0
	v_mov_b32_e32 v6, 0x21ff8
	ds_read_b32 v6, v6
	v_readlane_b32 s98, v253, 39
	v_readlane_b32 s99, v253, 40
	s_nop 4
	s_waitcnt lgkmcnt(0)
	v_readfirstlane_b32 s100, v6
	s_cmp_eq_u32 s100, 0
	s_cbranch_scc0 .Lxb_b1_full
	v_readlane_b32 s100, v254, 53
	s_bitcmp0_b32 s100, 0
	s_cbranch_scc0 .Lxb_b1_full
	v_mov_b32_e32 v6, 0x21ffc
	ds_write_b32 v6, v4
	s_cbranch_vccnz .Lxb_b1_lnl
	buffer_inv sc1
	s_waitcnt vmcnt(0)
	global_atomic_add v177, v238, s[98:99]
	s_branch .Lxb_b1_done

; #define LAS __attribute__((address_space(3)))
; __device__ __forceinline__ void mixb_item(const Args& A, int li, int item, LAS unsigned char* lds, int tid, int lane, int wave) {
;     const int row0 = item * 32, bb = row0 >> 13, pos0 = row0 & 8191;
;     const bf16_t* Gb = (const bf16_t*)(A.ws + WS_GB); bf16_t* CAT = (bf16_t*)(A.ws + WS_CAT);
;     const float* cw = A.in[10] + (size_t)li * 31 * 512; const float* cb = A.in[11] + li * 512; const float* ng = A.in[12] + li * 512; const float* nb = A.in[13] + li * 512;
;     LAS float* cv = (LAS float*)(lds + 65536);
;     {
;         u32x4 st[8];
; #pragma unroll
;         for (int i = 0; i < 8; ++i) { const int idx = tid + NTHR * i, row = idx >> 6, ch = idx & 63, pos = pos0 - 15 + row; const bool ok = idx < 62 * 64 && pos >= 0 && pos < SEQ;
;             st[i] = ok ? *(const u32x4*)(Gb + ((size_t)bb * SEQ + (ok ? pos : pos0)) * 512 + ch * 8) : (u32x4){0u, 0u, 0u, 0u}; }
; __global__ void __launch_bounds__(NTHR, 2) mega_fwd(Args A) {
;     ...
;         if (even) { for (int it = bx; it < 768; it += G) {
;     ...
;  if (it < 256) { mixa_item(A, li, it, lds, tid, lane, wave);
;     ...
;  mixa_item(A, li, it, lds, tid, lane, wave);
;     ...
;  }
;     ...
;  if (it >= 256) { mixb_item(A, li, it - 256, lds, tid, lane, wave);
;     ...
;  mixb_item(A, li, it - 256, lds, tid, lane, wave);
;     ...
;  }
.LBB0_440:
	s_cmpk_lt_i32 s2, 0x100
	s_cbranch_scc1 .LBB0_437
	s_and_b32 s14, s2, 7
	s_lshl_b32 s14, s14, 6
	s_bfe_u32 s100, s2, 0x50003
	s_or_b32 s14, s14, s100
	s_lshr_b32 s100, s2, 8
	s_add_i32 s100, s100, -1
	s_lshl_b32 s100, s100, 5
	s_or_b32 s14, s14, s100
	s_and_b32 s98, s14, 63
	s_add_i32 s14, s14, 0x100
	s_lshl_b32 s14, s14, 5
	s_cmp_eq_u32 s98, 0
	s_cbranch_scc1 .Lxh_wait
	s_cmp_eq_u32 s98, 63
	s_cbranch_scc0 .Lxh_go
.Lxh_wait:
	v_readfirstlane_b32 s100, v240
	s_cmp_lt_u32 s100, 64
	s_cbranch_scc0 .Lxh_join
	v_mov_b32_e32 v58, 0x21ffc
	ds_read_b32 v58, v58
	v_readlane_b32 s98, v253, 39
	v_readlane_b32 s99, v253, 40
	s_mov_b32 s100, 0
	s_waitcnt lgkmcnt(0)
	s_nop 4
.Lxh_spin:
	global_load_dword v59, v177, s[98:99] sc1
	s_waitcnt vmcnt(0)
	v_cmp_ge_u32_e32 vcc, v59, v58
	s_cbranch_vccnz .Lxh_join
	s_sleep 1
	s_add_i32 s100, s100, 1
	s_cmp_lt_u32 s100, 0x40000
	s_cbranch_scc1 .Lxh_spin
.Lxh_join:
	s_barrier
.Lxh_go:
	s_and_b32 s20, s14, 0x1fe0
	s_add_i32 s20, s20, -15
	v_add_u32_e32 v1, s20, v156
	s_movk_i32 s21, 0x2000
	s_add_i32 s11, s14, 0xffffe000
	v_cmp_gt_u32_e32 vcc, s21, v1
	s_and_b32 s14, s11, 0x2000
	s_and_b64 s[22:23], s[0:1], vcc
	v_mov_b32_e32 v0, 0
	v_mov_b32_e32 v4, 0
	v_mov_b32_e32 v5, 0
	v_mov_b32_e32 v6, 0
	v_mov_b32_e32 v7, 0
	s_and_saveexec_b64 s[34:35], s[22:23]
	s_cbranch_execz .LBB0_443
	v_or_b32_e32 v1, s14, v1
	v_lshlrev_b32_e32 v2, 10, v1
	v_mov_b32_e32 v3, v177
	v_lshl_add_u64 v[2:3], v[120:121], 0, v[2:3]
	global_load_dwordx4 v[4:7], v[2:3], off
